# cv17 + idle workgroups of the G3 (64 WGs) and G4 (128 WGs) sample-unit tails convert 1024 / 2048 next-layer weight blocks
# baseline (speedup 1.0000x reference)
.Lcv_site_p2:
	s_cmp_gt_u32 s98, 2
	s_cbranch_scc1 .Lcv_site_tail
	s_add_u32 s9, s30, 2
	s_mul_i32 s9, s9, 0x4180
	s_sub_u32 s8, s9, 0x4180
	s_cmp_eq_u32 s30, 0
	s_cselect_b32 s8, 0x1680, s8
	s_add_u32 s8, s8, s31
	s_mov_b32 s10, s66
	s_cmp_eq_u32 s3, 0x100
	s_cselect_b32 s32, 9472, 0
	s_sub_u32 s9, s9, s32
	s_branch .Lcv_go
.Lcv_site_tail:
	s_cmp_eq_u32 s3, 0x100
	s_cbranch_scc0 .Lcv_exit0
	s_cmp_eq_u32 s98, 3
	s_cbranch_scc0 .Lcv_site_t4
	s_cmp_eq_u32 s30, 0
	s_cbranch_scc1 .Lcv_exit0
	s_add_u32 s9, s30, 1
	s_movk_i32 s47, 216
	s_movk_i32 s48, 3200
	s_movk_i32 s49, 3200
	s_branch .Lcv_site_tc
.Lcv_site_t4:
	s_cmp_eq_u32 s30, 3
	s_cbranch_scc1 .Lcv_exit0
	s_add_u32 s9, s30, 2
	s_cmp_eq_u32 s98, 4
	s_cbranch_scc0 .Lcv_site_t5
	s_movk_i32 s47, 216
	s_mov_b32 s48, 0
	s_movk_i32 s49, 3200
	s_branch .Lcv_site_tc
.Lcv_site_t5:
	s_cmp_eq_u32 s98, 5
	s_cbranch_scc0 .Lcv_site_t6
	s_movk_i32 s47, 192
	s_movk_i32 s48, 8448
	s_movk_i32 s49, 1024
	s_branch .Lcv_site_tc
.Lcv_site_t6:
	s_movk_i32 s47, 128
	s_movk_i32 s48, 6400
	s_movk_i32 s49, 2048
.Lcv_site_tc:
	s_cmp_lt_u32 s2, s47
	s_cbranch_scc1 .Lcv_exit0
	s_cmp_eq_u32 s49, 0
	s_cbranch_scc1 .Lcv_exit0
	s_mul_i32 s9, s9, 0x4180
	s_sub_u32 s9, s9, s48
	s_sub_u32 s8, s9, s49
	s_sub_u32 s32, s2, s47
	s_lshl_b32 s32, s32, 3
	s_add_u32 s32, s32, s29
	s_add_u32 s8, s8, s32
	s_sub_u32 s10, 0x100, s47
	s_lshl_b32 s10, s10, 3

.Lcv_exit0:
.Lcv_exit:
	s_waitcnt vmcnt(0) lgkmcnt(0)
	v_readlane_b32 s4, v254, 0
	v_readlane_b32 s5, v254, 1
	v_readlane_b32 s6, v254, 2
	v_readlane_b32 s7, v254, 3
	v_readlane_b32 s8, v254, 4
	v_readlane_b32 s9, v254, 5
	v_readlane_b32 s10, v254, 6
	v_readlane_b32 s11, v254, 7
	v_readlane_b32 s12, v254, 8
	v_readlane_b32 s13, v254, 9
	v_readlane_b32 s14, v254, 10
	v_readlane_b32 s15, v254, 11
	v_readlane_b32 s16, v254, 12
	v_readlane_b32 s17, v254, 13
	v_readlane_b32 s18, v254, 14
	v_readlane_b32 s19, v254, 15
	v_readlane_b32 s20, v254, 16
	v_readlane_b32 s21, v254, 17
	v_readlane_b32 s22, v254, 18
	v_readlane_b32 s23, v254, 19
	v_readlane_b32 s24, v254, 20
	v_readlane_b32 s25, v254, 21
	v_readlane_b32 s26, v254, 22
	v_readlane_b32 s27, v254, 23
	v_readlane_b32 s28, v254, 24
	v_readlane_b32 s29, v254, 25
	v_readlane_b32 s30, v254, 26
	v_readlane_b32 s31, v254, 27
	v_readlane_b32 s32, v254, 28
	v_readlane_b32 s33, v254, 29
	v_readlane_b32 s34, v254, 30
	v_readlane_b32 s35, v254, 31
	v_readlane_b32 s36, v254, 32
	v_readlane_b32 s37, v254, 33
	v_readlane_b32 s38, v254, 34
	v_readlane_b32 s39, v254, 35
	v_readlane_b32 s40, v254, 36
	v_readlane_b32 s41, v254, 37
	v_readlane_b32 s42, v254, 38
	v_readlane_b32 s43, v254, 39
	v_readlane_b32 s44, v254, 40
	v_readlane_b32 s45, v254, 41
	v_readlane_b32 s46, v254, 42
	v_readlane_b32 s47, v254, 43
	v_readlane_b32 s48, v254, 44
	v_readlane_b32 s49, v254, 45
	v_readlane_b32 s50, v254, 46
	v_readlane_b32 s51, v254, 47
	v_readlane_b32 s52, v254, 48
	v_readlane_b32 s53, v254, 49
	s_nop 4
	s_cmp_eq_u32 s98, 0
	s_cbranch_scc1 .Lcv_ret0
	s_cmp_eq_u32 s98, 1
	s_cbranch_scc1 .Lcv_ret1
	s_cmp_eq_u32 s98, 2
	s_cbranch_scc1 .Lcv_ret2
	s_cmp_eq_u32 s98, 3
	s_cbranch_scc1 .Lcv_ret3
	s_cmp_eq_u32 s98, 4
	s_cbranch_scc1 .Lcv_ret4
	s_cmp_eq_u32 s98, 5
	s_cbranch_scc1 .Lcv_ret5
	s_branch .Lcv_ret6

.LBB0_1358:
	s_waitcnt vmcnt(0)
	v_readlane_b32 s60, v252, 49
	s_barrier
	s_mov_b32 s98, 5
	s_branch .Lcv_entry
.Lcv_ret5:
.LBB0_1359:
	s_waitcnt lgkmcnt(0)
	v_readlane_b32 s0, v252, 50
	s_add_i32 s6, s0, 5
	s_cmp_ge_i32 s6, s63
	s_cbranch_scc1 .LBB0_1409
	s_waitcnt vmcnt(0)
	s_waitcnt vmcnt(0)
	s_barrier
	s_mov_b64 s[0:1], exec
	v_readlane_b32 s4, v252, 43
	v_readlane_b32 s5, v252, 44
	s_and_b64 s[4:5], s[0:1], s[4:5]
	s_mov_b64 exec, s[4:5]
	s_cbranch_execz .LBB0_1408
	v_readlane_b32 s4, v253, 2
	s_waitcnt vmcnt(0) expcnt(0) lgkmcnt(0)
	s_nop 0
	v_mov_b32_e32 v2, s4
	ds_read_b32 v4, v2
	ds_read_b32 v2, v2 offset:4
	s_waitcnt lgkmcnt(1)
	v_cmp_ne_u32_e32 vcc, 0, v4
	s_cbranch_vccnz .LBB0_1376
	v_readlane_b32 s8, v253, 0
	v_readlane_b32 s9, v253, 1
	s_load_dwordx2 s[4:5], s[8:9], 0x4
	s_mov_b32 s13, 1
	s_waitcnt lgkmcnt(0)
	s_mul_i32 s12, s4, s3
	s_mul_i32 s12, s12, s5
	s_branch .LBB0_1364

.LBB0_1521:
	s_waitcnt vmcnt(0)
	v_readlane_b32 s60, v252, 49
	s_barrier
	s_mov_b32 s98, 6
	s_branch .Lcv_entry
.Lcv_ret6:
.LBB0_1522:
	v_readlane_b32 s0, v252, 50
	s_add_i32 s6, s0, 7
	s_cmp_ge_i32 s6, s63
	s_cbranch_scc1 .LBB0_1534
	s_waitcnt vmcnt(0)
	s_waitcnt vmcnt(0) lgkmcnt(0)
	s_barrier
	s_mov_b64 s[0:1], exec
	v_readlane_b32 s4, v252, 43
	v_readlane_b32 s5, v252, 44
	s_and_b64 s[4:5], s[0:1], s[4:5]
	s_mov_b32 s71, 0x200000
	s_mov_b64 exec, s[4:5]
	s_cbranch_execz .LBB0_1572
	v_readlane_b32 s4, v253, 2
	s_waitcnt vmcnt(0) expcnt(0) lgkmcnt(0)
	s_nop 0
	v_mov_b32_e32 v2, s4
	ds_read_b32 v4, v2
	ds_read_b32 v2, v2 offset:4
	s_waitcnt lgkmcnt(1)
	v_cmp_ne_u32_e32 vcc, 0, v4
	s_cbranch_vccnz .LBB0_1540
	v_readlane_b32 s8, v253, 0
	v_readlane_b32 s9, v253, 1
	s_load_dwordx2 s[4:5], s[8:9], 0x4
	s_mov_b32 s13, 1
	s_waitcnt lgkmcnt(0)
	s_mul_i32 s12, s4, s3
	s_mul_i32 s12, s12, s5
	s_branch .LBB0_1527
